# SWA sample unit: the four f32-cache staging iterations peeled, their 8 K/V loads issued together
# baseline (speedup 1.0000x reference)
.LBB0_85:
	s_or_b64 exec, exec, s[4:5]
	v_mov_b32_e32 v0, s86
	s_waitcnt lgkmcnt(0)
	s_barrier
	ds_read_b32 v0, v0
	s_mov_b64 s[4:5], -1
	s_waitcnt lgkmcnt(0)
	v_cmp_lt_i32_e32 vcc, s58, v0
	v_readfirstlane_b32 s0, v0
	s_cbranch_vccnz .LBB0_82
	s_bitcmp0_b32 s0, 0
	s_cbranch_scc1 .LBB0_112
	v_readlane_b32 s4, v255, 2
	v_readlane_b32 s5, v255, 3
	s_andn2_b64 vcc, exec, s[4:5]
	s_cbranch_vccnz .LBB0_111
	s_mov_b64 s[6:7], s[94:95]
	s_add_u32 s4, s6, 0xc700000
	s_addc_u32 s5, s7, 0
	v_mov_b32_e32 v8, v191
	s_and_b32 s25, s0, -8
	s_movk_i32 s8, 0x880
	s_bfe_u32 s24, s0, 0x20001
	s_addk_i32 s25, 0x4000
	s_mov_b64 s[16:17], s[92:93]
	s_mov_b64 s[18:19], s[92:93]
	v_cmp_gt_i32_e32 vcc, s8, v8
	s_and_saveexec_b64 s[8:9], vcc
	v_readlane_b32 s88, v254, 12
	s_movk_i32 s54, 0xc00
	s_movk_i32 s55, 0x110
	v_readlane_b32 s64, v253, 60
	s_movk_i32 s65, 0x240
	v_readlane_b32 s66, v253, 61
	v_readlane_b32 s90, v254, 14
	v_readlane_b32 s91, v254, 15
	v_readlane_b32 s89, v254, 13
	v_readlane_b32 s92, v254, 16
	v_readlane_b32 s93, v254, 17
	v_readlane_b32 s94, v254, 18
	v_readlane_b32 s95, v254, 19
	s_cbranch_execz .LBB0_97
	s_ashr_i32 s10, s0, 3
	s_ashr_i32 s11, s10, 31
	s_lshl_b64 s[20:21], s[10:11], 17
	s_lshl_b32 s10, s24, 8
	v_readlane_b32 s72, v253, 42
	s_or_b32 s20, s20, s10
	v_readlane_b32 s78, v253, 48
	v_readlane_b32 s79, v253, 49
	s_add_u32 s10, s78, s20
	v_readlane_b32 s80, v253, 50
	s_addc_u32 s11, s79, s21
	v_readlane_b32 s81, v253, 51
	s_add_u32 s12, s80, s20
	s_addc_u32 s13, s81, s21
	s_mul_i32 s15, s25, 0xc00
	s_mul_hi_i32 s14, s25, 0xc00
	s_add_u32 s15, s4, s15
	s_addc_u32 s22, s5, s14
	s_lshl_b32 s14, s24, 7
	s_add_u32 s14, s15, s14
	s_addc_u32 s15, s22, 0
	s_add_u32 s16, s16, s20
	s_addc_u32 s17, s17, s21
	s_add_u32 s16, s16, 0xae00000
	s_addc_u32 s17, s17, 0
	s_add_u32 s18, s18, s20
	s_addc_u32 s19, s19, s21
	s_add_u32 s18, s18, 0xbe00000
	s_addc_u32 s19, s19, 0
	v_and_b32_e32 v10, 15, v8
	v_lshlrev_b32_e32 v10, 4, v10
	v_lshrrev_b32_e32 v11, 4, v8
	v_lshl_add_u32 v13, v11, 10, v10
	v_mul_u32_u24_e32 v14, 0x110, v11
	v_add_u32_e32 v14, v14, v10
	v_lshl_add_u32 v15, v11, 8, v10
	global_load_dwordx4 v[194:197], v13, s[10:11]
	global_load_dwordx4 v[198:201], v13, s[12:13]
	v_add_u32_e32 v0, 0x8000, v13
	global_load_dwordx4 v[202:205], v0, s[10:11]
	global_load_dwordx4 v[206:209], v0, s[12:13]
	v_add_u32_e32 v1, 0x10000, v13
	global_load_dwordx4 v[210:213], v1, s[10:11]
	global_load_dwordx4 v[214:217], v1, s[12:13]
	v_add_u32_e32 v2, 0x18000, v13
	global_load_dwordx4 v[218:221], v2, s[10:11]
	global_load_dwordx4 v[222:225], v2, s[12:13]
	v_add_u32_e32 v3, 0xffffe000, v13
	v_add_u32_e32 v4, 0x6000, v13
	v_add_u32_e32 v5, 0xe000, v13
	v_add_u32_e32 v6, 0x16000, v13
	s_waitcnt vmcnt(0)
	ds_write_b128 v14, v[194:197]
	ds_write_b128 v15, v[198:201] offset:36992
	ds_write_b128 v14, v[202:205] offset:8704
	ds_write_b128 v15, v[206:209] offset:45184
	ds_write_b128 v14, v[210:213] offset:17408
	ds_write_b128 v15, v[214:217] offset:53376
	ds_write_b128 v14, v[218:221] offset:26112
	ds_write_b128 v15, v[222:225] offset:61568
	global_store_dwordx4 v4, v[202:205], s[16:17] nt
	global_store_dwordx4 v4, v[206:209], s[18:19] nt
	global_store_dwordx4 v5, v[210:213], s[16:17] nt
	global_store_dwordx4 v5, v[214:217], s[18:19] nt
	global_store_dwordx4 v6, v[218:221], s[16:17] nt
	global_store_dwordx4 v6, v[222:225], s[18:19] nt
	v_cmp_lt_u32_e32 vcc, 0x7f, v8
	s_and_saveexec_b64 s[22:23], vcc
	global_store_dwordx4 v3, v[194:197], s[16:17] nt
	global_store_dwordx4 v3, v[198:201], s[18:19] nt
	s_or_b64 exec, exec, s[22:23]
	v_add_u32_e32 v12, 0x800, v8
	v_lshlrev_b32_e32 v9, 2, v12
	s_mov_b64 s[20:21], 0
	v_readlane_b32 s73, v253, 43
	v_readlane_b32 s74, v253, 44
	v_readlane_b32 s75, v253, 45
	v_readlane_b32 s76, v253, 46
	v_readlane_b32 s77, v253, 47
	v_readlane_b32 s82, v253, 52
	v_readlane_b32 s83, v253, 53
	v_readlane_b32 s84, v253, 54
	v_readlane_b32 s85, v253, 55
	v_readlane_b32 s86, v253, 56
	v_readlane_b32 s87, v253, 57
	v_cmp_gt_u32_e32 vcc, 0x80, v8
	s_nop 1
	s_and_b64 exec, exec, vcc
	s_cbranch_execz .LBB0_97
	s_branch .LBB0_91
